# phase 1: DFT operand-image items read cos/sin from the LDS trig table (two-element software-pipelined loop) instead of evaluating sincos per element on one wave
# speedup vs baseline: 1.0058x; 1.0012x over previous
.LBB0_103:
	s_cmp_lg_u32 s0, 0
	s_cbranch_scc0 .LBB0_120
	s_cmp_lg_u32 s0, 1
	s_cselect_b64 s[34:35], -1, 0
	s_cmp_eq_u32 s0, 1
	s_cselect_b64 vcc, -1, 0
	s_and_b64 s[0:1], vcc, exec
	s_movk_i32 s1, 0x4000
	s_mov_b32 s0, 0x184000
	s_cselect_b32 s83, s1, 0x2000
	s_cselect_b32 s0, s0, 0x18c800
	v_max_u32_e32 v6, s83, v3
	s_add_u32 s76, s48, s0
	v_add_u32_e32 v6, v6, v17
	s_movk_i32 s0, 0xbf
	s_addc_u32 s77, s49, 0
	s_branch .Ltab_fast
.Ltab_fast:
	s_lshr_b32 s100, s83, 7
	v_mov_b32_e32 v7, v2
	v_lshrrev_b32_e32 v8, 7, v7
	v_mul_lo_u32 v9, v8, v7
	v_and_b32_e32 v9, 63, v9
	v_lshlrev_b32_e32 v9, 2, v9
	v_add_u32_e32 v9, 0x10800, v9
	ds_read_b32 v14, v9
	ds_read_b32 v10, v9 offset:256
.Ltab_loop:
	v_add_u32_e32 v16, 64, v7
	v_lshrrev_b32_e32 v18, 7, v16
	v_mul_lo_u32 v18, v18, v16
	v_and_b32_e32 v18, 63, v18
	v_lshlrev_b32_e32 v18, 2, v18
	v_add_u32_e32 v18, 0x10800, v18
	ds_read_b32 v21, v18
	ds_read_b32 v22, v18 offset:256
	v_lshrrev_b32_e32 v8, 7, v7
	v_and_b32_e32 v6, 0x7f, v7
	s_waitcnt lgkmcnt(2)
	s_and_b64 vcc, exec, s[34:35]
	s_cbranch_vccnz .Ltab_s2_a
	v_cmp_gt_u32_e32 vcc, 64, v6
	v_cndmask_b32_e64 v23, -v10, v14, vcc
	v_cndmask_b32_e32 v20, v14, v10, vcc
	v_cmp_gt_u32_e32 vcc, s45, v7
	v_cndmask_b32_e64 v24, -v20, v23, vcc
	s_branch .Ltab_st_a
.Ltab_s2_a:
	v_cmp_gt_u32_e32 vcc, 64, v6
	v_cndmask_b32_e32 v24, v10, v14, vcc
.Ltab_st_a:
	v_bfe_u32 v9, v24, 16, 1
	v_add3_u32 v24, v24, v9, s47
	v_mad_u32_u24 v8, v8, s59, v6
	v_mov_b32_e32 v9, 0
	v_lshl_add_u64 v[8:9], v[8:9], 1, s[76:77]
	global_store_short_d16_hi v[8:9], v24, off
	v_add_u32_e32 v7, 64, v16
	v_lshrrev_b32_e32 v18, 7, v7
	v_mul_lo_u32 v18, v18, v7
	v_and_b32_e32 v18, 63, v18
	v_lshlrev_b32_e32 v18, 2, v18
	v_add_u32_e32 v18, 0x10800, v18
	ds_read_b32 v14, v18
	ds_read_b32 v10, v18 offset:256
	v_lshrrev_b32_e32 v8, 7, v16
	v_and_b32_e32 v6, 0x7f, v16
	s_waitcnt lgkmcnt(2)
	s_and_b64 vcc, exec, s[34:35]
	s_cbranch_vccnz .Ltab_s2_b
	v_cmp_gt_u32_e32 vcc, 64, v6
	v_cndmask_b32_e64 v23, -v22, v21, vcc
	v_cndmask_b32_e32 v20, v21, v22, vcc
	v_cmp_gt_u32_e32 vcc, s45, v16
	v_cndmask_b32_e64 v24, -v20, v23, vcc
	s_branch .Ltab_st_b
.Ltab_s2_b:
	v_cmp_gt_u32_e32 vcc, 64, v6
	v_cndmask_b32_e32 v24, v22, v21, vcc
.Ltab_st_b:
	v_bfe_u32 v9, v24, 16, 1
	v_add3_u32 v24, v24, v9, s47
	v_mad_u32_u24 v8, v8, s59, v6
	v_mov_b32_e32 v9, 0
	v_lshl_add_u64 v[8:9], v[8:9], 1, s[76:77]
	global_store_short_d16_hi v[8:9], v24, off
	s_sub_u32 s100, s100, 1
	s_cmp_lg_u32 s100, 0
	s_cbranch_scc1 .Ltab_loop
	s_waitcnt lgkmcnt(0)
	s_branch .LBB0_102
	v_cmp_lt_u32_e64 s[4:5], s0, v6
	s_mov_b64 s[6:7], -1
	v_mov_b32_e32 v7, v2
	s_and_saveexec_b64 s[78:79], s[4:5]
	s_cbranch_execz .LBB0_108
	v_lshrrev_b32_e32 v6, 6, v6
	v_add_u32_e32 v40, 1, v6
	v_and_b32_e32 v41, 0x7fffffc, v40
	v_mov_b64_e32 v[8:9], v[4:5]
	s_mov_b64 s[80:81], 0
	v_mov_b32_e32 v42, v41
	v_mov_b64_e32 v[6:7], v[2:3]
